# as the code-prefetch version, with the last seam's touch clamped inside the kernel's own code
# baseline (speedup 1.0000x reference)
.Lxb7_ic:
	s_add_u32 s10, s10, .Lxb7_done-.Lxb7_ic
	s_addc_u32 s11, s11, 0
	s_mov_b32 s12, .Lxb8_top-.Lxb7_done
	s_lshr_b32 s12, s12, 12
	s_mov_b64 exec, -1
	v_mbcnt_lo_u32_b32 v8, -1, 0
	v_mbcnt_hi_u32_b32 v8, -1, v8
	v_lshlrev_b32_e32 v8, 6, v8
